# v27 + GLA log-sigmoid: dead denormal/inf handling of the generic logf expansion removed (argument in [1,2], bit-identical)
# speedup vs baseline: 1.0003x; 1.0003x over previous
; #define LAS __attribute__((address_space(3)))
; __device__ __forceinline__ float fexp(float x) { return __builtin_amdgcn_exp2f(x * 1.4426950408889634f); }
; __device__ __forceinline__ void gla_unit(LAS char* lds0, int b, int h, int dvh, bf16_t* Z, bf16_t* OT, const float* afw, const float* afb, const float* abw, const float* abb, bool dry) {
;     ...
;             f32x16 zc;
; #pragma unroll
;             for (int r = 0; r < 16; ++r) zc[r] = bias;
;             const bf16x8 a = *(const LAS bf16x8*)(lds + G_A16 + (32 * I + r32) * 32 + hi * 16);
;             zc = __builtin_amdgcn_mfma_f32_32x32x16_bf16(a, w2b, zc, 0, 0, 0);
; #pragma unroll
;             for (int r = 0; r < 16; ++r) { const float z = zc[r]; cs[r] = (fminf(z, 0.f) - __logf(1.f + fexp(-fabsf(z)))) * (1.f / 16.f); }
;         }
; #pragma unroll
;         for (int g = 0; g < 4; ++g) { cs[4 * g + 1] += cs[4 * g]; cs[4 * g + 2] += cs[4 * g + 1]; cs[4 * g + 3] += cs[4 * g + 2]; }
;         float run = 0.f;
; #pragma unroll
;         for (int g = 0; g < 4; ++g) {
;             const float mine = cs[4 * g + 3]; const float oth = __shfl_xor(mine, 32);
;             const float off = run + (hi ? oth : 0.f);
; #pragma unroll
;             for (int j = 0; j < 4; ++j) cs[4 * g + j] += off;
;             run += mine + oth;
;         }
;         if (hi == 0) ((LAS float*)(lds + G_TOT))[I * 64 + 32 * J + r32] = run;
.LBB0_412:
	ds_read_b128 v[50:53], v156 offset:64512
	s_waitcnt lgkmcnt(0)
	v_mfma_f32_32x32x16_bf16 v[34:49], v[50:53], v[66:69], v[2:17]
	s_nop 11
	v_max_f32_e32 v50, v34, v34
	v_mul_f32_e64 v34, |v34|, s33
	v_exp_f32_e32 v34, v34
	v_min_f32_e32 v50, 0, v50
	v_add_f32_e32 v34, 1.0, v34
	v_log_f32_e32 v34, v34
	s_nop 0
	v_mul_f32_e32 v51, 0x3f317217, v34
	v_fma_f32 v51, v34, s19, -v51
	v_fmac_f32_e32 v51, 0x3377d1cf, v34
	v_fmac_f32_e32 v51, 0x3f317217, v34
	v_sub_f32_e32 v34, v50, v51
	v_max_f32_e32 v50, v35, v35
	v_mul_f32_e64 v35, |v35|, s33
	v_exp_f32_e32 v35, v35
	v_min_f32_e32 v50, 0, v50
	v_mul_f32_e32 v34, 0x3d800000, v34
	v_add_f32_e32 v35, 1.0, v35
	v_log_f32_e32 v35, v35
	s_nop 0
	v_mul_f32_e32 v51, 0x3f317217, v35
	v_fma_f32 v51, v35, s19, -v51
	v_fmac_f32_e32 v51, 0x3377d1cf, v35
	v_fmac_f32_e32 v51, 0x3f317217, v35
	v_sub_f32_e32 v35, v50, v51
	v_max_f32_e32 v50, v36, v36
	v_mul_f32_e64 v36, |v36|, s33
	v_exp_f32_e32 v36, v36
	v_min_f32_e32 v50, 0, v50
	v_add_f32_e32 v36, 1.0, v36
	v_log_f32_e32 v36, v36
	s_nop 0
	v_mul_f32_e32 v51, 0x3f317217, v36
	v_fma_f32 v51, v36, s19, -v51
	v_fmac_f32_e32 v51, 0x3377d1cf, v36
	v_fmac_f32_e32 v51, 0x3f317217, v36
	v_sub_f32_e32 v36, v50, v51
	v_max_f32_e32 v50, v37, v37
	v_mul_f32_e64 v37, |v37|, s33
	v_exp_f32_e32 v37, v37
	v_min_f32_e32 v50, 0, v50
	v_add_f32_e32 v37, 1.0, v37
	v_log_f32_e32 v37, v37
	s_nop 0
	v_mul_f32_e32 v51, 0x3f317217, v37
	v_fma_f32 v51, v37, s19, -v51
	v_fmac_f32_e32 v51, 0x3377d1cf, v37
	v_fmac_f32_e32 v51, 0x3f317217, v37
	v_sub_f32_e32 v50, v50, v51
	v_max_f32_e32 v37, v38, v38
	v_mul_f32_e64 v38, |v38|, s33
	v_exp_f32_e32 v38, v38
	v_min_f32_e32 v37, 0, v37
	v_add_f32_e32 v38, 1.0, v38
	v_log_f32_e32 v38, v38
	s_nop 0
	v_mul_f32_e32 v51, 0x3f317217, v38
	v_fma_f32 v51, v38, s19, -v51
	v_fmac_f32_e32 v51, 0x3377d1cf, v38
	v_fmac_f32_e32 v51, 0x3f317217, v38
	v_sub_f32_e32 v37, v37, v51
	v_max_f32_e32 v38, v39, v39
	v_mul_f32_e64 v39, |v39|, s33
	v_exp_f32_e32 v39, v39
	v_min_f32_e32 v38, 0, v38
	v_mul_f32_e32 v37, 0x3d800000, v37
	v_add_f32_e32 v39, 1.0, v39
	v_log_f32_e32 v39, v39
	s_nop 0
	v_mul_f32_e32 v51, 0x3f317217, v39
	v_fma_f32 v51, v39, s19, -v51
	v_fmac_f32_e32 v51, 0x3377d1cf, v39
	v_fmac_f32_e32 v51, 0x3f317217, v39
	v_sub_f32_e32 v38, v38, v51
	v_max_f32_e32 v39, v40, v40
	v_mul_f32_e64 v40, |v40|, s33
	v_exp_f32_e32 v40, v40
	v_min_f32_e32 v39, 0, v39
	v_add_f32_e32 v40, 1.0, v40
	v_log_f32_e32 v40, v40
	s_nop 0
	v_mul_f32_e32 v51, 0x3f317217, v40
	v_fma_f32 v51, v40, s19, -v51
	v_fmac_f32_e32 v51, 0x3377d1cf, v40
	v_fmac_f32_e32 v51, 0x3f317217, v40
	v_sub_f32_e32 v39, v39, v51
	v_max_f32_e32 v40, v41, v41
	v_mul_f32_e64 v41, |v41|, s33
	v_exp_f32_e32 v41, v41
	v_min_f32_e32 v40, 0, v40
	v_add_f32_e32 v41, 1.0, v41
	v_log_f32_e32 v41, v41
	s_nop 0
	v_mul_f32_e32 v51, 0x3f317217, v41
	v_fma_f32 v51, v41, s19, -v51
	v_fmac_f32_e32 v51, 0x3377d1cf, v41
	v_fmac_f32_e32 v51, 0x3f317217, v41
	v_sub_f32_e32 v41, v40, v51
	v_max_f32_e32 v40, v42, v42
	v_mul_f32_e64 v42, |v42|, s33
	v_exp_f32_e32 v42, v42
	v_min_f32_e32 v40, 0, v40
	v_add_f32_e32 v42, 1.0, v42
	v_log_f32_e32 v42, v42
	s_nop 0
	v_mul_f32_e32 v51, 0x3f317217, v42
	v_fma_f32 v51, v42, s19, -v51
	v_fmac_f32_e32 v51, 0x3377d1cf, v42
	v_fmac_f32_e32 v51, 0x3f317217, v42
	v_sub_f32_e32 v40, v40, v51
	v_max_f32_e32 v42, v43, v43
	v_mul_f32_e64 v43, |v43|, s33
	v_exp_f32_e32 v43, v43
	v_min_f32_e32 v42, 0, v42
	v_mul_f32_e32 v40, 0x3d800000, v40
	v_add_f32_e32 v43, 1.0, v43
	v_log_f32_e32 v43, v43
	s_nop 0
	v_mul_f32_e32 v51, 0x3f317217, v43
	v_fma_f32 v51, v43, s19, -v51
	v_fmac_f32_e32 v51, 0x3377d1cf, v43
	v_fmac_f32_e32 v51, 0x3f317217, v43
	v_sub_f32_e32 v51, v42, v51
	v_mul_f32_e64 v43, |v44|, s33
	v_exp_f32_e32 v43, v43
	v_max_f32_e32 v42, v44, v44
	v_min_f32_e32 v42, 0, v42
	v_add_f32_e32 v43, 1.0, v43
	v_log_f32_e32 v43, v43
	s_nop 0
	v_mul_f32_e32 v44, 0x3f317217, v43
	v_fma_f32 v44, v43, s19, -v44
	v_fmac_f32_e32 v44, 0x3377d1cf, v43
	v_fmac_f32_e32 v44, 0x3f317217, v43
	v_sub_f32_e32 v52, v42, v44
	v_mul_f32_e64 v43, |v45|, s33
	v_exp_f32_e32 v43, v43
	v_max_f32_e32 v42, v45, v45
	v_min_f32_e32 v42, 0, v42
	v_add_f32_e32 v43, 1.0, v43
	v_log_f32_e32 v43, v43
	s_nop 0
	v_mul_f32_e32 v44, 0x3f317217, v43
	v_fma_f32 v44, v43, s19, -v44
	v_fmac_f32_e32 v44, 0x3377d1cf, v43
	v_fmac_f32_e32 v44, 0x3f317217, v43
	v_sub_f32_e32 v53, v42, v44
	v_mul_f32_e64 v43, |v46|, s33
	v_exp_f32_e32 v43, v43
	v_max_f32_e32 v42, v46, v46
	v_min_f32_e32 v42, 0, v42
	v_add_f32_e32 v43, 1.0, v43
	v_log_f32_e32 v43, v43
	s_nop 0
	v_mul_f32_e32 v44, 0x3f317217, v43
	v_fma_f32 v44, v43, s19, -v44
	v_fmac_f32_e32 v44, 0x3377d1cf, v43
	v_fmac_f32_e32 v44, 0x3f317217, v43
	v_sub_f32_e32 v42, v42, v44
	v_mul_f32_e64 v43, |v47|, s33
	v_exp_f32_e32 v43, v43
	v_mul_f32_e32 v46, 0x3d800000, v42
	v_max_f32_e32 v42, v47, v47
	v_min_f32_e32 v42, 0, v42
	v_add_f32_e32 v43, 1.0, v43
	v_log_f32_e32 v43, v43
	s_nop 0
	v_mul_f32_e32 v44, 0x3f317217, v43
	v_fma_f32 v44, v43, s19, -v44
	v_fmac_f32_e32 v44, 0x3377d1cf, v43
	v_fmac_f32_e32 v44, 0x3f317217, v43
	v_sub_f32_e32 v47, v42, v44
	v_mul_f32_e64 v43, |v48|, s33
	v_exp_f32_e32 v43, v43
	v_max_f32_e32 v42, v48, v48
	v_min_f32_e32 v42, 0, v42
	v_add_f32_e32 v43, 1.0, v43
	v_log_f32_e32 v43, v43
	s_nop 0
	v_mul_f32_e32 v44, 0x3f317217, v43
	v_fma_f32 v44, v43, s19, -v44
	v_fmac_f32_e32 v44, 0x3377d1cf, v43
	v_fmac_f32_e32 v44, 0x3f317217, v43
	v_sub_f32_e32 v54, v42, v44
	v_mul_f32_e64 v43, |v49|, s33
	v_exp_f32_e32 v43, v43
	v_max_f32_e32 v42, v49, v49
	v_min_f32_e32 v42, 0, v42
	v_add_f32_e32 v43, 1.0, v43
	v_log_f32_e32 v43, v43
	s_nop 0
	v_mul_f32_e32 v44, 0x3f317217, v43
	v_fma_f32 v44, v43, s19, -v44
	v_fmac_f32_e32 v44, 0x3377d1cf, v43
	v_fmac_f32_e32 v44, 0x3f317217, v43
	v_mov_b32_e32 v43, v44
	v_fmamk_f32 v44, v35, 0x3d800000, v34
	v_sub_f32_e32 v55, v42, v43
	v_fmamk_f32 v45, v36, 0x3d800000, v44
	v_fmamk_f32 v42, v38, 0x3d800000, v37
	v_fmamk_f32 v49, v50, 0x3d800000, v45
	v_fmamk_f32 v43, v39, 0x3d800000, v42
	v_fmamk_f32 v38, v51, 0x3d800000, v40
	v_fmamk_f32 v41, v41, 0x3d800000, v43
	v_fmamk_f32 v39, v52, 0x3d800000, v38
	v_fmamk_f32 v35, v47, 0x3d800000, v46
	ds_bpermute_b32 v51, v119, v49
	v_fmamk_f32 v48, v53, 0x3d800000, v39
	v_fmamk_f32 v36, v54, 0x3d800000, v35
	ds_bpermute_b32 v53, v119, v41
	v_fmamk_f32 v47, v55, 0x3d800000, v36
	ds_bpermute_b32 v55, v119, v48
	ds_bpermute_b32 v56, v119, v47
	s_waitcnt lgkmcnt(3)
	v_add_f32_e32 v50, v49, v51
	v_add_f32_e32 v50, 0, v50
	s_waitcnt lgkmcnt(2)
	v_add_f32_e32 v52, v41, v53
	v_add_f32_e32 v52, v52, v50
	s_waitcnt lgkmcnt(1)
	v_add_f32_e32 v54, v48, v55
	v_add_f32_e32 v54, v54, v52
	s_and_saveexec_b64 s[76:77], s[38:39]
	s_cbranch_execz .LBB0_414
	s_waitcnt lgkmcnt(0)
	v_add_f32_e32 v57, v47, v56
	v_add_f32_e32 v57, v57, v54
	ds_write_b32 v121, v57
